# e25: e24 + P1 rebalance: the 128 S5-table workgroups (the long ones of P1) hand their one weight-transpose item each to the other 128 workgroups (vcu>=128 runs item 320+(vcu-128) through the same code
# speedup vs baseline: 1.0076x; 1.0038x over previous
; #define SUB(i, ...) do { if (PROBE_PH == phk && PROBE_SUB == (i)) { __syncthreads(); tp0 = __builtin_amdgcn_s_memrealtime(); } __VA_ARGS__ if (PROBE_PH == phk && PROBE_SUB == (i)) { asm volatile("s_waitcnt vmcnt(0)" ::: "memory"); __syncthreads(); tp1 = __builtin_amdgcn_s_memrealtime(); } } while (0)
; __global__ void __launch_bounds__(NTHREADS, 2) mk_fwd(Args a) {
;     ...
;         SUB(2, if (vcu < 128) transpose_dispatch((320 + vcu) * 8 + wave, a.in[7], a.in[20], a.in[18], a.in[8], a.ws, scr, lane);
;                else { const int b2 = vcu - 128;
;                    for (int it = 448 + 3 * b2; it < 448 + 3 * b2 + 3; ++it) transpose_dispatch(it * 8 + wave, a.in[7], a.in[20], a.in[18], a.in[8], a.ws, scr, lane);
;                    if (b2 < 16) transpose_dispatch((832 + b2) * 8 + wave, a.in[7], a.in[20], a.in[18], a.in[8], a.ws, scr, lane); } );
.LBB0_212:
	s_sub_i32 s6, s81, 0x80
	s_lshl_b32 s6, s6, 3
	s_add_i32 s6, s6, s53
	s_mov_b64 s[2:3], -1
